# grid-barrier spin loops poll without the 64-cycle sleep
# baseline (speedup 1.0000x reference)
.LBB0_14:
	s_sleep 0
	global_load_dword v2, v0, s[6:7] offset:32 sc1
	s_waitcnt vmcnt(0)
	v_and_b32_e32 v2, 0xffff0000, v2
	v_cmp_ne_u32_e32 vcc, v2, v1
	s_or_b64 s[8:9], vcc, s[8:9]
	s_andn2_b64 exec, exec, s[8:9]
	s_cbranch_execnz .LBB0_14

.LBB0_88:
	global_load_dword v15, v16, s[8:9] sc1
	global_load_dword v0, v16, s[10:11] sc1
	global_load_dword v1, v16, s[12:13] sc1
	global_load_dword v2, v16, s[14:15] sc1
	global_load_dword v3, v16, s[16:17] sc1
	global_load_dword v4, v16, s[18:19] sc1
	global_load_dword v5, v16, s[20:21] sc1
	global_load_dword v6, v16, s[22:23] sc1
	global_load_dword v7, v16, s[24:25] sc1
	global_load_dword v8, v16, s[26:27] sc1
	global_load_dword v9, v16, s[28:29] sc1
	global_load_dword v10, v16, s[30:31] sc1
	global_load_dword v11, v16, s[34:35] sc1
	global_load_dword v12, v16, s[36:37] sc1
	global_load_dword v13, v16, s[38:39] sc1
	global_load_dword v14, v16, s[40:41] sc1
	s_mov_b64 s[42:43], -1
	s_mov_b64 s[44:45], -1
	s_waitcnt vmcnt(14)
	v_add_u32_e32 v17, v0, v15
	s_waitcnt vmcnt(13)
	v_add_u32_e32 v17, v17, v1
	s_waitcnt vmcnt(12)
	v_add_u32_e32 v17, v17, v2
	s_waitcnt vmcnt(11)
	v_add_u32_e32 v17, v17, v3
	s_waitcnt vmcnt(10)
	v_add_u32_e32 v17, v17, v4
	s_waitcnt vmcnt(9)
	v_add_u32_e32 v17, v17, v5
	s_waitcnt vmcnt(8)
	v_add_u32_e32 v17, v17, v6
	s_waitcnt vmcnt(7)
	v_add_u32_e32 v17, v17, v7
	s_waitcnt vmcnt(6)
	v_add_u32_e32 v17, v17, v8
	s_waitcnt vmcnt(5)
	v_add_u32_e32 v17, v17, v9
	s_waitcnt vmcnt(4)
	v_add_u32_e32 v17, v17, v10
	s_waitcnt vmcnt(3)
	v_add_u32_e32 v17, v17, v11
	s_waitcnt vmcnt(2)
	v_add_u32_e32 v17, v17, v12
	s_waitcnt vmcnt(1)
	v_add_u32_e32 v17, v17, v13
	s_waitcnt vmcnt(0)
	v_add_u32_e32 v17, v17, v14
	v_cmp_eq_u32_e32 vcc, s2, v17
	s_cbranch_vccnz .LBB0_87
	s_and_b32 s42, s3, 0xff
	s_cmp_eq_u32 s42, 0
	s_mov_b64 s[42:43], -1
	s_mov_b64 s[46:47], -1
	s_sleep 0
	s_cbranch_scc1 .LBB0_92
	s_and_b64 vcc, exec, s[46:47]
	s_cbranch_vccz .LBB0_87

.LBB0_106:
	s_and_b32 s3, s2, 0xff
	s_mov_b64 s[20:21], -1
	s_cmp_lg_u32 s3, 0
	s_mov_b64 s[24:25], -1
	s_sleep 0
	s_cbranch_scc0 .LBB0_109
	s_and_b64 vcc, exec, s[24:25]
	s_cbranch_vccz .LBB0_105

.LBB0_123:
	s_and_b32 s3, s2, 0xff
	s_cmp_lg_u32 s3, 0
	s_mov_b64 s[22:23], -1
	s_sleep 0
	s_cbranch_scc0 .LBB0_126
	s_mov_b64 s[24:25], -1
	s_and_b64 vcc, exec, s[22:23]
	s_cbranch_vccz .LBB0_122

.LBB0_2978:
	global_load_dword v15, v16, s[4:5] sc1
	global_load_dword v0, v16, s[6:7] sc1
	global_load_dword v1, v16, s[8:9] sc1
	global_load_dword v2, v16, s[10:11] sc1
	global_load_dword v3, v16, s[12:13] sc1
	global_load_dword v4, v16, s[14:15] sc1
	global_load_dword v5, v16, s[16:17] sc1
	global_load_dword v6, v16, s[18:19] sc1
	global_load_dword v7, v16, s[20:21] sc1
	global_load_dword v8, v16, s[22:23] sc1
	global_load_dword v9, v16, s[24:25] sc1
	global_load_dword v10, v16, s[26:27] sc1
	global_load_dword v11, v16, s[28:29] sc1
	global_load_dword v12, v16, s[30:31] sc1
	global_load_dword v13, v16, s[34:35] sc1
	global_load_dword v14, v16, s[36:37] sc1
	s_mov_b64 s[38:39], -1
	s_mov_b64 s[40:41], -1
	s_waitcnt vmcnt(14)
	v_add_u32_e32 v17, v0, v15
	s_waitcnt vmcnt(13)
	v_add_u32_e32 v17, v17, v1
	s_waitcnt vmcnt(12)
	v_add_u32_e32 v17, v17, v2
	s_waitcnt vmcnt(11)
	v_add_u32_e32 v17, v17, v3
	s_waitcnt vmcnt(10)
	v_add_u32_e32 v17, v17, v4
	s_waitcnt vmcnt(9)
	v_add_u32_e32 v17, v17, v5
	s_waitcnt vmcnt(8)
	v_add_u32_e32 v17, v17, v6
	s_waitcnt vmcnt(7)
	v_add_u32_e32 v17, v17, v7
	s_waitcnt vmcnt(6)
	v_add_u32_e32 v17, v17, v8
	s_waitcnt vmcnt(5)
	v_add_u32_e32 v17, v17, v9
	s_waitcnt vmcnt(4)
	v_add_u32_e32 v17, v17, v10
	s_waitcnt vmcnt(3)
	v_add_u32_e32 v17, v17, v11
	s_waitcnt vmcnt(2)
	v_add_u32_e32 v17, v17, v12
	s_waitcnt vmcnt(1)
	v_add_u32_e32 v17, v17, v13
	s_waitcnt vmcnt(0)
	v_add_u32_e32 v17, v17, v14
	v_cmp_eq_u32_e32 vcc, s44, v17
	s_cbranch_vccnz .LBB0_2977
	s_and_b32 s38, s45, 0xff
	s_cmp_eq_u32 s38, 0
	s_mov_b64 s[38:39], -1
	s_mov_b64 s[42:43], -1
	s_sleep 0
	s_cbranch_scc1 .LBB0_2982
	s_and_b64 vcc, exec, s[42:43]
	s_cbranch_vccz .LBB0_2977

.LBB0_2996:
	s_and_b32 s18, s22, 0xff
	s_mov_b64 s[16:17], -1
	s_cmp_lg_u32 s18, 0
	s_mov_b64 s[20:21], -1
	s_sleep 0
	s_cbranch_scc0 .LBB0_2999
	s_and_b64 vcc, exec, s[20:21]
	s_cbranch_vccz .LBB0_2995

.LBB0_3013:
	s_and_b32 s16, s22, 0xff
	s_cmp_lg_u32 s16, 0
	s_mov_b64 s[18:19], -1
	s_sleep 0
	s_cbranch_scc0 .LBB0_3016
	s_mov_b64 s[20:21], -1
	s_and_b64 vcc, exec, s[18:19]
	s_cbranch_vccz .LBB0_3012
